# same as the previous version plus sc1 (L1 bypass) on the ssm_p3 parked-y reloads: no reliance on L1 write-hit behaviour when the per-wave parking slots are reused
# speedup vs baseline: 1.0084x; 1.0025x over previous
; __device__ __forceinline__ unsigned pk2(float lo, float hi) { const f32x2 v = {lo, hi}; return __builtin_bit_cast(unsigned, __builtin_convertvector(v, bf16x2_t)); }
; __device__ __forceinline__ float bflo(unsigned w) { return __uint_as_float(w << 16); }
; __device__ __forceinline__ float bfhi(unsigned w) { return __uint_as_float(w & 0xffff0000u); }
; #define LDS_FENCE() asm volatile("s_waitcnt lgkmcnt(0)" ::: "memory")
; template <bool BWD, int MODE  >
; __device__ __forceinline__ void ssm_pass(const bf16* proj, int rowbase, int g, const bf16x8* BBp, const bf16x8* CCp, float ar, float ai, float& sr, float& si,
;                                          LAS unsigned* XS, int lane, f32x4* ysc, const float* Dp, bf16* zbuf) {
;     ...
;     for (int c = 0; c < 16; ++c) {
;         const int ch = BWD ? 15 - c : c;
;         bf16x8 unext = ucur;
;         if (c < 15) unext = *(const bf16x8*)(up + (size_t)(BWD ? ch - 1 : ch + 1) * 32 * DIN);
;         f32x4 y0 = (f32x4){0.f, 0.f, 0.f, 0.f}, y1 = y0; bf16 uvl[8];
;         if (MODE == 2) {
;             y0 = ysc[(ch * 2 + 0) * 64 + lane]; y1 = ysc[(ch * 2 + 1) * 64 + lane];
; #pragma unroll
;             for (int q = 0; q < 8; ++q) uvl[q] = proj[(size_t)(rowbase + 32 * ch + 16 * (q >> 2) + 4 * (lane >> 4) + (q & 3)) * DIN + 768 + g * 16 + (lane & 15)];
;         }
;         f32x16 z16;
; #pragma unroll
;         for (int r = 0; r < 16; ++r) z16[r] = 0.f;
;         const f32x16 x0 = __builtin_amdgcn_mfma_f32_32x32x16_bf16(ucur, bb[0], z16, 0, 0, 0);
;         const f32x16 x1 = __builtin_amdgcn_mfma_f32_32x32x16_bf16(ucur, bb[1], z16, 0, 0, 0);
;         const f32x16 x2 = __builtin_amdgcn_mfma_f32_32x32x16_bf16(ucur, bb[2], z16, 0, 0, 0);
;         const f32x16 x3 = __builtin_amdgcn_mfma_f32_32x32x16_bf16(ucur, bb[3], z16, 0, 0, 0);
; #pragma unroll
;         for (int r = 0; r < 16; ++r) { const int t = crow(r, hi); XS[t * XS_STRIDE + ql] = pk2(x0[r], x2[r]); XS[t * XS_STRIDE + 32 + ql] = pk2(x1[r], x3[r]); }
;         LDS_FENCE();
; #pragma unroll
;         for (int tt = 0; tt < 32; ++tt) {
;             const int t = BWD ? 31 - tt : tt;
;             const unsigned v = XS[t * XS_STRIDE + lane];
;             const float nr = fmaf(ar, sr, fmaf(-ai, si, bflo(v))), ni = fmaf(ar, si, fmaf(ai, sr, bfhi(v)));
;             sr = nr; si = ni;
;             if (MODE > 0) XS[t * XS_STRIDE + lane] = pk2(sr, si);
.Lp3n_nopfb:
	global_load_dwordx4 v[188:191], v225, s[78:79] offset:1024 sc1
	global_load_dwordx4 v[192:195], v225, s[78:79] sc1
	global_load_ushort v196, v206, s[6:7]
	global_load_ushort v197, v206, s[6:7] offset:2560
	global_load_ushort v198, v206, s[80:81]
	global_load_ushort v199, v206, s[80:81] offset:2560
	global_load_ushort v200, v207, s[6:7]
	global_load_ushort v201, v207, s[6:7] offset:-2560
	global_load_ushort v202, v207, s[82:83]
	global_load_ushort v203, v207, s[82:83] offset:-2560
	v_mfma_f32_32x32x16_bf16 v[2:17], v[130:133], v[66:69], 0
	v_mfma_f32_32x32x16_bf16 v[18:33], v[130:133], v[70:73], 0
	v_mfma_f32_32x32x16_bf16 v[34:49], v[130:133], v[74:77], 0
	v_mfma_f32_32x32x16_bf16 v[50:65], v[130:133], v[78:81], 0
	v_mfma_f32_32x32x16_bf16 v[2:17], v[134:137], v[82:85], v[2:17]
	v_mfma_f32_32x32x16_bf16 v[18:33], v[134:137], v[86:89], v[18:33]
	v_mfma_f32_32x32x16_bf16 v[34:49], v[134:137], v[90:93], v[34:49]
	v_mfma_f32_32x32x16_bf16 v[50:65], v[134:137], v[94:97], v[50:65]
	s_nop 15
	s_nop 7
	v_fmac_f32_e32 v2, v150, v153
	v_fmac_f32_e32 v18, v151, v155
	v_fmac_f32_e32 v34, v147, v152
	v_fmac_f32_e32 v50, v149, v154
	v_fmac_f32_e32 v2, v146, v152
	v_fmac_f32_e32 v18, v148, v154
	v_fmac_f32_e32 v34, v146, v153
	v_fmac_f32_e32 v50, v148, v155
	v_fmac_f32_e32 v3, v150, v34
	v_fmac_f32_e32 v19, v151, v50
	v_fmac_f32_e32 v35, v147, v2
	v_fmac_f32_e32 v51, v149, v18
	v_fmac_f32_e32 v3, v146, v2
	v_fmac_f32_e32 v19, v148, v18
	v_fmac_f32_e32 v35, v146, v34
	v_fmac_f32_e32 v51, v148, v50
	v_cvt_pk_bf16_f32 v214, v2, v34
	v_cvt_pk_bf16_f32 v215, v18, v50
	ds_write2_b32 v158, v214, v215 offset0:0 offset1:32
	v_fmac_f32_e32 v4, v150, v35
	v_fmac_f32_e32 v20, v151, v51
	v_fmac_f32_e32 v36, v147, v3
	v_fmac_f32_e32 v52, v149, v19
	v_fmac_f32_e32 v4, v146, v3
	v_fmac_f32_e32 v20, v148, v19
	v_fmac_f32_e32 v36, v146, v35
	v_fmac_f32_e32 v52, v148, v51
	v_cvt_pk_bf16_f32 v216, v3, v35
	v_cvt_pk_bf16_f32 v217, v19, v51
	ds_write2_b32 v158, v216, v217 offset0:68 offset1:100
	v_fmac_f32_e32 v5, v150, v36
	v_fmac_f32_e32 v21, v151, v52
	v_fmac_f32_e32 v37, v147, v4
	v_fmac_f32_e32 v53, v149, v20
	v_fmac_f32_e32 v5, v146, v4
	v_fmac_f32_e32 v21, v148, v20
	v_fmac_f32_e32 v37, v146, v36
	v_fmac_f32_e32 v53, v148, v52
	v_cvt_pk_bf16_f32 v214, v4, v36
	v_cvt_pk_bf16_f32 v215, v20, v52
	ds_write2_b32 v158, v214, v215 offset0:136 offset1:168
	v_fmac_f32_e32 v6, v150, v37
	v_fmac_f32_e32 v22, v151, v53
	v_fmac_f32_e32 v38, v147, v5
	v_fmac_f32_e32 v54, v149, v21
	v_fmac_f32_e32 v6, v146, v5
	v_fmac_f32_e32 v22, v148, v21
	v_fmac_f32_e32 v38, v146, v37
	v_fmac_f32_e32 v54, v148, v53
	v_cvt_pk_bf16_f32 v216, v5, v37
	v_cvt_pk_bf16_f32 v217, v21, v53
	ds_write2_b32 v158, v216, v217 offset0:204 offset1:236
	v_fmac_f32_e32 v7, v150, v38
	v_fmac_f32_e32 v23, v151, v54
	v_fmac_f32_e32 v39, v147, v6
	v_fmac_f32_e32 v55, v149, v22
	v_fmac_f32_e32 v7, v146, v6
	v_fmac_f32_e32 v23, v148, v22
	v_fmac_f32_e32 v39, v146, v38
	v_fmac_f32_e32 v55, v148, v54
	v_cvt_pk_bf16_f32 v214, v6, v38
	v_cvt_pk_bf16_f32 v215, v22, v54
	ds_write2_b32 v159, v214, v215 offset0:0 offset1:32
	v_fmac_f32_e32 v8, v150, v39
	v_fmac_f32_e32 v24, v151, v55
	v_fmac_f32_e32 v40, v147, v7
	v_fmac_f32_e32 v56, v149, v23
	v_fmac_f32_e32 v8, v146, v7
	v_fmac_f32_e32 v24, v148, v23
	v_fmac_f32_e32 v40, v146, v39
	v_fmac_f32_e32 v56, v148, v55
	v_cvt_pk_bf16_f32 v216, v7, v39
	v_cvt_pk_bf16_f32 v217, v23, v55
	ds_write2_b32 v159, v216, v217 offset0:68 offset1:100
	v_fmac_f32_e32 v9, v150, v40
	v_fmac_f32_e32 v25, v151, v56
	v_fmac_f32_e32 v41, v147, v8
	v_fmac_f32_e32 v57, v149, v24
	v_fmac_f32_e32 v9, v146, v8
	v_fmac_f32_e32 v25, v148, v24
	v_fmac_f32_e32 v41, v146, v40
	v_fmac_f32_e32 v57, v148, v56
	v_cvt_pk_bf16_f32 v214, v8, v40
	v_cvt_pk_bf16_f32 v215, v24, v56
	ds_write2_b32 v159, v214, v215 offset0:136 offset1:168
	v_fmac_f32_e32 v10, v150, v41
	v_fmac_f32_e32 v26, v151, v57
	v_fmac_f32_e32 v42, v147, v9
	v_fmac_f32_e32 v58, v149, v25
	v_fmac_f32_e32 v10, v146, v9
	v_fmac_f32_e32 v26, v148, v25
	v_fmac_f32_e32 v42, v146, v41
	v_fmac_f32_e32 v58, v148, v57
	v_cvt_pk_bf16_f32 v216, v9, v41
	v_cvt_pk_bf16_f32 v217, v25, v57
	ds_write2_b32 v159, v216, v217 offset0:204 offset1:236
	v_fmac_f32_e32 v11, v150, v42
	v_fmac_f32_e32 v27, v151, v58
	v_fmac_f32_e32 v43, v147, v10
	v_fmac_f32_e32 v59, v149, v26
	v_fmac_f32_e32 v11, v146, v10
	v_fmac_f32_e32 v27, v148, v26
	v_fmac_f32_e32 v43, v146, v42
	v_fmac_f32_e32 v59, v148, v58
	v_cvt_pk_bf16_f32 v214, v10, v42
	v_cvt_pk_bf16_f32 v215, v26, v58
	ds_write2_b32 v160, v214, v215 offset0:0 offset1:32
	v_fmac_f32_e32 v12, v150, v43
	v_fmac_f32_e32 v28, v151, v59
	v_fmac_f32_e32 v44, v147, v11
	v_fmac_f32_e32 v60, v149, v27
	v_fmac_f32_e32 v12, v146, v11
	v_fmac_f32_e32 v28, v148, v27
	v_fmac_f32_e32 v44, v146, v43
	v_fmac_f32_e32 v60, v148, v59
	v_cvt_pk_bf16_f32 v216, v11, v43
	v_cvt_pk_bf16_f32 v217, v27, v59
	ds_write2_b32 v160, v216, v217 offset0:68 offset1:100
	v_fmac_f32_e32 v13, v150, v44
	v_fmac_f32_e32 v29, v151, v60
	v_fmac_f32_e32 v45, v147, v12
	v_fmac_f32_e32 v61, v149, v28
	v_fmac_f32_e32 v13, v146, v12
	v_fmac_f32_e32 v29, v148, v28
	v_fmac_f32_e32 v45, v146, v44
	v_fmac_f32_e32 v61, v148, v60
	v_cvt_pk_bf16_f32 v214, v12, v44
	v_cvt_pk_bf16_f32 v215, v28, v60
	ds_write2_b32 v160, v214, v215 offset0:136 offset1:168
	v_fmac_f32_e32 v14, v150, v45
	v_fmac_f32_e32 v30, v151, v61
	v_fmac_f32_e32 v46, v147, v13
	v_fmac_f32_e32 v62, v149, v29
	v_fmac_f32_e32 v14, v146, v13
	v_fmac_f32_e32 v30, v148, v29
	v_fmac_f32_e32 v46, v146, v45
	v_fmac_f32_e32 v62, v148, v61
	v_cvt_pk_bf16_f32 v216, v13, v45
	v_cvt_pk_bf16_f32 v217, v29, v61
	ds_write2_b32 v160, v216, v217 offset0:204 offset1:236
	v_fmac_f32_e32 v15, v150, v46
	v_fmac_f32_e32 v31, v151, v62
	v_fmac_f32_e32 v47, v147, v14
	v_fmac_f32_e32 v63, v149, v30
	v_fmac_f32_e32 v15, v146, v14
	v_fmac_f32_e32 v31, v148, v30
	v_fmac_f32_e32 v47, v146, v46
	v_fmac_f32_e32 v63, v148, v62
	v_cvt_pk_bf16_f32 v214, v14, v46
	v_cvt_pk_bf16_f32 v215, v30, v62
	ds_write2_b32 v161, v214, v215 offset0:0 offset1:32
	v_fmac_f32_e32 v16, v150, v47
	v_fmac_f32_e32 v32, v151, v63
	v_fmac_f32_e32 v48, v147, v15
	v_fmac_f32_e32 v64, v149, v31
	v_fmac_f32_e32 v16, v146, v15
	v_fmac_f32_e32 v32, v148, v31
	v_fmac_f32_e32 v48, v146, v47
	v_fmac_f32_e32 v64, v148, v63
	v_cvt_pk_bf16_f32 v216, v15, v47
	v_cvt_pk_bf16_f32 v217, v31, v63
	ds_write2_b32 v161, v216, v217 offset0:68 offset1:100
	v_fmac_f32_e32 v17, v150, v48
	v_fmac_f32_e32 v33, v151, v64
	v_fmac_f32_e32 v49, v147, v16
	v_fmac_f32_e32 v65, v149, v32
	v_fmac_f32_e32 v17, v146, v16
	v_fmac_f32_e32 v33, v148, v32
	v_fmac_f32_e32 v49, v146, v48
	v_fmac_f32_e32 v65, v148, v64
	v_cvt_pk_bf16_f32 v214, v16, v48
	v_cvt_pk_bf16_f32 v215, v32, v64
	ds_write2_b32 v161, v214, v215 offset0:136 offset1:168
	v_cvt_pk_bf16_f32 v216, v17, v49
	v_cvt_pk_bf16_f32 v217, v33, v65
	ds_write2_b32 v161, v216, v217 offset0:204 offset1:236
	v_mov_b32_e32 v152, v17
	v_mov_b32_e32 v153, v49
	v_mov_b32_e32 v154, v33
	v_mov_b32_e32 v155, v65
	s_waitcnt lgkmcnt(0)
; #define LAS __attribute__((address_space(3)))
; __device__ __forceinline__ unsigned f2bf(float f) { unsigned u = __builtin_bit_cast(unsigned, f); return (u + 0x7fffu + ((u >> 16) & 1u)) >> 16; }
; __device__ __forceinline__ float bf2f(bf16 v) { return __uint_as_float((unsigned)v << 16); }
; #define LDS_FENCE() asm volatile("s_waitcnt lgkmcnt(0)" ::: "memory")
; template <bool BWD, int MODE  >
; __device__ __forceinline__ void ssm_pass(const bf16* proj, int rowbase, int g, const bf16x8* BBp, const bf16x8* CCp, float ar, float ai, float& sr, float& si,
;                                          LAS unsigned* XS, int lane, f32x4* ysc, const float* Dp, bf16* zbuf) {
;     ...
;         if (MODE > 0) {
;             LDS_FENCE();
;             const LAS unsigned char* ab = (const LAS unsigned char*)XS + (lane & 15) * (XS_STRIDE * 4) + (lane >> 4) * 16;
; #pragma unroll
;             for (int kk = 0; kk < 4; ++kk) {
;                 const bf16x8 a0 = *(const LAS bf16x8*)(ab + kk * 64), a1 = *(const LAS bf16x8*)(ab + 16 * XS_STRIDE * 4 + kk * 64);
;                 y0 = __builtin_amdgcn_mfma_f32_16x16x32_bf16(a0, cc[kk], y0, 0, 0, 0);
;                 y1 = __builtin_amdgcn_mfma_f32_16x16x32_bf16(a1, cc[kk], y1, 0, 0, 0);
;             }
;             if (MODE == 1) { ysc[(ch * 2 + 0) * 64 + lane] = y0; ysc[(ch * 2 + 1) * 64 + lane] = y1; }
;             else {
;                 const int hcol = g * 16 + (lane & 15);
; #pragma unroll
;                 for (int rt = 0; rt < 2; ++rt)
; #pragma unroll
;                     for (int i = 0; i < 4; ++i) {
;                         const int row = rowbase + 32 * ch + 16 * rt + 4 * (lane >> 4) + i;
;                         const float uv = bf2f(uvl[rt * 4 + i]);
;                         const float y = (rt ? y1[i] : y0[i]) + dval * uv;
;                         const float zz = y * __builtin_amdgcn_rcpf(1.0f + __builtin_amdgcn_exp2f(-2.3022082f * (y + 0.044715f * y * y * y)));
;                         zbuf[(size_t)row * 512 + hcol] = (bf16)f2bf(zz);
;                     }
	ds_read_b128 v[226:229], v178 offset:0
	ds_read_b128 v[242:245], v178 offset:4352
	ds_read_b128 v[230:233], v178 offset:64
	ds_read_b128 v[246:249], v178 offset:4416
	ds_read_b128 v[234:237], v178 offset:128
	ds_read_b128 v[250:253], v178 offset:4480
	ds_read_b128 v[238:241], v178 offset:192
	ds_read_b128 v[210:213], v178 offset:4544
	s_waitcnt lgkmcnt(6)
	v_mfma_f32_16x16x32_bf16 v[180:183], v[226:229], v[98:101], 0
	v_mfma_f32_16x16x32_bf16 v[184:187], v[242:245], v[114:117], 0
	s_waitcnt lgkmcnt(4)
	v_mfma_f32_16x16x32_bf16 v[180:183], v[230:233], v[102:105], v[180:183]
	v_mfma_f32_16x16x32_bf16 v[184:187], v[246:249], v[118:121], v[184:187]
	s_waitcnt lgkmcnt(2)
	v_mfma_f32_16x16x32_bf16 v[180:183], v[234:237], v[106:109], v[180:183]
	v_mfma_f32_16x16x32_bf16 v[184:187], v[250:253], v[122:125], v[184:187]
	s_waitcnt lgkmcnt(0)
	v_mfma_f32_16x16x32_bf16 v[180:183], v[238:241], v[110:113], v[180:183]
	v_mfma_f32_16x16x32_bf16 v[184:187], v[210:213], v[126:129], v[184:187]
	s_waitcnt vmcnt(0)
	v_mov_b32_e32 v130, v138
	v_mov_b32_e32 v131, v139
	v_mov_b32_e32 v132, v140
	v_mov_b32_e32 v133, v141
	v_mov_b32_e32 v134, v142
	v_mov_b32_e32 v135, v143
	v_mov_b32_e32 v136, v144
	v_mov_b32_e32 v137, v145
	s_nop 7
	v_add_f32_e32 v180, v180, v191
	v_add_f32_e32 v181, v181, v190
	v_add_f32_e32 v182, v182, v189
	v_add_f32_e32 v183, v183, v188
	v_add_f32_e32 v184, v184, v195
	v_add_f32_e32 v185, v185, v194
	v_add_f32_e32 v186, v186, v193
	v_add_f32_e32 v187, v187, v192
	v_lshlrev_b32_e32 v196, 16, v196
	v_lshlrev_b32_e32 v197, 16, v197
	v_lshlrev_b32_e32 v198, 16, v198
	v_lshlrev_b32_e32 v199, 16, v199
	v_lshlrev_b32_e32 v200, 16, v200
	v_lshlrev_b32_e32 v201, 16, v201
	v_lshlrev_b32_e32 v202, 16, v202
	v_lshlrev_b32_e32 v203, 16, v203
	v_fmac_f32_e32 v180, v208, v196
	v_fmac_f32_e32 v181, v208, v197
	v_fmac_f32_e32 v182, v208, v198
	v_fmac_f32_e32 v183, v208, v199
	v_fmac_f32_e32 v184, v208, v200
	v_fmac_f32_e32 v185, v208, v201
	v_fmac_f32_e32 v186, v208, v202
	v_fmac_f32_e32 v187, v208, v203
	v_mul_f32_e32 v226, 0x3d372713, v180
	v_mul_f32_e32 v227, 0x3d372713, v181
	v_mul_f32_e32 v228, 0x3d372713, v182
	v_mul_f32_e32 v229, 0x3d372713, v183
	v_mul_f32_e32 v230, 0x3d372713, v184
	v_mul_f32_e32 v231, 0x3d372713, v185
	v_mul_f32_e32 v232, 0x3d372713, v186
	v_mul_f32_e32 v233, 0x3d372713, v187
	v_mul_f32_e32 v226, v180, v226
	v_mul_f32_e32 v227, v181, v227
	v_mul_f32_e32 v228, v182, v228
	v_mul_f32_e32 v229, v183, v229
	v_mul_f32_e32 v230, v184, v230
	v_mul_f32_e32 v231, v185, v231
	v_mul_f32_e32 v232, v186, v232
	v_mul_f32_e32 v233, v187, v233
	v_fma_f32 v226, v180, v226, v180
	v_fma_f32 v227, v181, v227, v181
	v_fma_f32 v228, v182, v228, v182
	v_fma_f32 v229, v183, v229, v183
	v_fma_f32 v230, v184, v230, v184
	v_fma_f32 v231, v185, v231, v185
	v_fma_f32 v232, v186, v232, v186
	v_fma_f32 v233, v187, v233, v187
	v_mul_f32_e32 v226, 0xc0135761, v226
	v_mul_f32_e32 v227, 0xc0135761, v227
	v_mul_f32_e32 v228, 0xc0135761, v228
	v_mul_f32_e32 v229, 0xc0135761, v229
	v_mul_f32_e32 v230, 0xc0135761, v230
	v_mul_f32_e32 v231, 0xc0135761, v231
	v_mul_f32_e32 v232, 0xc0135761, v232
	v_mul_f32_e32 v233, 0xc0135761, v233
	v_exp_f32_e32 v226, v226
	v_exp_f32_e32 v227, v227
	v_exp_f32_e32 v228, v228
	v_exp_f32_e32 v229, v229
	v_exp_f32_e32 v230, v230
	v_exp_f32_e32 v231, v231
	v_exp_f32_e32 v232, v232
	v_exp_f32_e32 v233, v233
	v_add_f32_e32 v226, 1.0, v226
	v_add_f32_e32 v227, 1.0, v227
	v_add_f32_e32 v228, 1.0, v228
	v_add_f32_e32 v229, 1.0, v229
	v_add_f32_e32 v230, 1.0, v230
	v_add_f32_e32 v231, 1.0, v231
	v_add_f32_e32 v232, 1.0, v232
	v_add_f32_e32 v233, 1.0, v233
	v_rcp_f32_e32 v226, v226
	v_rcp_f32_e32 v227, v227
	v_rcp_f32_e32 v228, v228
	v_rcp_f32_e32 v229, v229
	v_rcp_f32_e32 v230, v230
	v_rcp_f32_e32 v231, v231
	v_rcp_f32_e32 v232, v232
	v_rcp_f32_e32 v233, v233
	v_mul_f32_e32 v226, v180, v226
	v_mul_f32_e32 v227, v181, v227
	v_mul_f32_e32 v228, v182, v228
	v_mul_f32_e32 v229, v183, v229
	v_mul_f32_e32 v230, v184, v230
	v_mul_f32_e32 v231, v185, v231
	v_mul_f32_e32 v232, v186, v232
	v_mul_f32_e32 v233, v187, v233
	v_cvt_pk_bf16_f32 v226, v226, v226
	v_cvt_pk_bf16_f32 v227, v227, v227
	v_cvt_pk_bf16_f32 v228, v228, v228
	v_cvt_pk_bf16_f32 v229, v229, v229
	v_cvt_pk_bf16_f32 v230, v230, v230
	v_cvt_pk_bf16_f32 v231, v231, v231
	v_cvt_pk_bf16_f32 v232, v232, v232
	v_cvt_pk_bf16_f32 v233, v233, v233
	global_store_short v204, v226, s[8:9]
	global_store_short v204, v227, s[8:9] offset:1024
	global_store_short v204, v228, s[8:9] offset:2048
	global_store_short v204, v229, s[8:9] offset:3072
	global_store_short v205, v230, s[8:9]
	global_store_short v205, v231, s[8:9] offset:-1024
	global_store_short v205, v232, s[8:9] offset:-2048
	global_store_short v205, v233, s[8:9] offset:-3072
	v_add_u32_e32 v204, 0x4000, v204
	v_add_u32_e32 v205, 0xffffc000, v205
	v_add_u32_e32 v206, 0xa000, v206
	v_add_u32_e32 v207, 0xffff6000, v207
	s_sub_u32 s78, s78, 0x800
	s_subb_u32 s79, s79, 0
	s_add_i32 s32, s32, 1
	s_cmp_lt_u32 s32, 8
	s_cbranch_scc1 .Lp3n_loopb
	v_add_u32_e32 v204, 0x10000, v204
	v_add_u32_e32 v205, 0x30000, v205
	v_add_u32_e32 v206, 0x28000, v206
	v_add_u32_e32 v207, 0x78000, v207
	s_add_i32 s45, s45, 1
	s_cmp_lt_u32 s45, 4
	s_cbranch_scc1 .Lp3n_block
	s_add_i32 s58, s58, s20
	s_cmpk_gt_i32 s58, 0xff
	s_cbranch_scc0 .Lp3n_task
